# lora LDS-copy loop rolled (3-step body x4) plus one s_nop after the phase so the code behind it keeps its 8-byte phase
# speedup vs baseline: 1.0161x; 1.0011x over previous
; #define LAS __attribute__((address_space(3)))
; __device__ __forceinline__ unsigned pk2(float lo, float hi) { f32x2 v = {lo, hi}; bf16x2_t b = __builtin_convertvector(v, bf16x2_t); return __builtin_bit_cast(unsigned, b); }
; __device__ __forceinline__ float sigmoidf_(float x) { return frcp(1.f + fexp2(-1.4426950408889634f * x)); }
; __device__ __forceinline__ void phase_lora(const Ctx& p, LAS unsigned char* lds) {
;     ...
;             const int tt = lane >> 2, cq = lane & 3, row = r0 + tt;
; #pragma unroll
;             for (int j = 0; j < 8; ++j) {
;                 const int c = cq * 64 + j * 8;
;                 float m8[8], z[8];
; #pragma unroll
;                 for (int e = 0; e < 8; ++e) m8[e] = mu[c + e];
;                 zshift8(p, ZRW, row, 1536 + c, m8, z);
; #pragma unroll
;                 for (int e = 0; e < 8; ++e) z[e] = cq == 0 ? tanhf(z[e]) : (cq == 1 ? z[e] : sigmoidf_(z[e]));
;                 u32x4 w; w.x = pk2(z[0], z[1]); w.y = pk2(z[2], z[3]); w.z = pk2(z[4], z[5]); w.w = pk2(z[6], z[7]);
;                 *(LAS u32x4*)(X + tt * 264 + c) = w;
;             }
;         }
;         asm volatile("s_waitcnt lgkmcnt(0)" ::: "memory");
;         bf16x8 bx[8];
; #pragma unroll
;         for (int ks = 0; ks < 8; ++ks) bx[ks] = *(const LAS bf16x8*)(X + q * 264 + ks * 32 + 8 * g);
;         const int row = r0 + q;
;         struct WF { bf16x8 w[2], a[2], gq[4]; f32x4 w0, a0; };
.Llora_nf7:
	v_sub_f32_e32 v152, v152, v144
	v_sub_f32_e32 v153, v153, v145
	v_sub_f32_e32 v154, v154, v146
	v_sub_f32_e32 v155, v155, v147
	v_sub_f32_e32 v156, v156, v148
	v_sub_f32_e32 v157, v157, v149
	v_sub_f32_e32 v158, v158, v150
	v_sub_f32_e32 v159, v159, v151
	v_fmac_f32_e32 v144, v152, v136
	v_fmac_f32_e32 v145, v153, v137
	v_fmac_f32_e32 v146, v154, v138
	v_fmac_f32_e32 v147, v155, v139
	v_fmac_f32_e32 v148, v156, v140
	v_fmac_f32_e32 v149, v157, v141
	v_fmac_f32_e32 v150, v158, v142
	v_fmac_f32_e32 v151, v159, v143
	v_mul_f32_e32 v152, v7, v144
	v_mul_f32_e32 v153, v7, v145
	v_mul_f32_e32 v154, v7, v146
	v_mul_f32_e32 v155, v7, v147
	v_mul_f32_e32 v156, v7, v148
	v_mul_f32_e32 v157, v7, v149
	v_mul_f32_e32 v158, v7, v150
	v_mul_f32_e32 v159, v7, v151
	v_exp_f32_e32 v152, v152
	v_exp_f32_e32 v153, v153
	v_exp_f32_e32 v154, v154
	v_exp_f32_e32 v155, v155
	v_exp_f32_e32 v156, v156
	v_exp_f32_e32 v157, v157
	v_exp_f32_e32 v158, v158
	v_exp_f32_e32 v159, v159
	v_add_f32_e32 v152, 1.0, v152
	v_add_f32_e32 v153, 1.0, v153
	v_add_f32_e32 v154, 1.0, v154
	v_add_f32_e32 v155, 1.0, v155
	v_add_f32_e32 v156, 1.0, v156
	v_add_f32_e32 v157, 1.0, v157
	v_add_f32_e32 v158, 1.0, v158
	v_add_f32_e32 v159, 1.0, v159
	v_rcp_f32_e32 v152, v152
	v_rcp_f32_e32 v153, v153
	v_rcp_f32_e32 v154, v154
	v_rcp_f32_e32 v155, v155
	v_rcp_f32_e32 v156, v156
	v_rcp_f32_e32 v157, v157
	v_rcp_f32_e32 v158, v158
	v_rcp_f32_e32 v159, v159
	v_fma_f32 v152, v152, v8, v9
	v_fma_f32 v153, v153, v8, v9
	v_fma_f32 v154, v154, v8, v9
	v_fma_f32 v155, v155, v8, v9
	v_fma_f32 v156, v156, v8, v9
	v_fma_f32 v157, v157, v8, v9
	v_fma_f32 v158, v158, v8, v9
	v_fma_f32 v159, v159, v8, v9
	v_cndmask_b32_e64 v152, v152, v144, s[48:49]
	v_cndmask_b32_e64 v153, v153, v145, s[48:49]
	v_cndmask_b32_e64 v154, v154, v146, s[48:49]
	v_cndmask_b32_e64 v155, v155, v147, s[48:49]
	v_cndmask_b32_e64 v156, v156, v148, s[48:49]
	v_cndmask_b32_e64 v157, v157, v149, s[48:49]
	v_cndmask_b32_e64 v158, v158, v150, s[48:49]
	v_cndmask_b32_e64 v159, v159, v151, s[48:49]
	v_cvt_pk_bf16_f32 v160, v152, v153
	v_cvt_pk_bf16_f32 v161, v154, v155
	v_cvt_pk_bf16_f32 v162, v156, v157
	v_cvt_pk_bf16_f32 v163, v158, v159
	ds_write_b128 v6, v[160:163] offset:112
	s_waitcnt lgkmcnt(0)
	ds_read_b128 v[184:187], v14 offset:0
	ds_read_b128 v[188:191], v14 offset:64
	ds_read_b128 v[192:195], v14 offset:128
	ds_read_b128 v[196:199], v14 offset:192
	ds_read_b128 v[200:203], v14 offset:256
	ds_read_b128 v[204:207], v14 offset:320
	ds_read_b128 v[208:211], v14 offset:384
	ds_read_b128 v[212:215], v14 offset:448
	s_lshl_b32 s2, s26, 4
	v_add_u32_e32 v137, s2, v10
	v_lshl_add_u32 v132, v11, 4, v10
	v_lshlrev_b32_e32 v132, 4, v132
	v_mov_b32_e32 v133, v132
	v_lshlrev_b32_e32 v134, 4, v11
	v_lshlrev_b32_e32 v135, 11, v137
	v_lshl_add_u32 v135, v11, 4, v135
	v_lshlrev_b32_e32 v136, 10, v137
	v_lshl_add_u32 v136, v11, 3, v136
	s_cmp_lg_u32 s57, 0
	s_cbranch_scc1 .Llora_single
	s_lshl_b32 s2, s56, 15
	v_add_u32_e32 v132, s2, v132
	s_lshl_b32 s2, s56, 16
	v_add_u32_e32 v133, s2, v133
	s_lshl_b32 s2, s56, 10
	v_add_u32_e32 v134, s2, v134
	v_add_u32_e32 v135, s2, v135
	s_lshl_b32 s2, s56, 9
	v_add_u32_e32 v136, s2, v136
	s_and_b32 s60, s27, 3
	s_cmp_gt_u32 s60, 1
	s_cselect_b32 s3, 1, 0
	s_movk_i32 s64, 0x800
	s_lshl_b32 s64, s64, s3
	s_lshl_b32 s2, s60, 16
	s_cmp_eq_u32 s60, 2
	s_cselect_b32 s2, 0x20000, s2
	s_cmp_eq_u32 s60, 3
	s_cselect_b32 s2, 0x20800, s2
	s_lshl_b32 s3, s64, 4
	s_mul_i32 s3, s3, s56
	s_add_u32 s2, s2, s3
	s_add_u32 s62, s24, s2
	s_addc_u32 s63, s25, 0
	s_lshl_b32 s2, s56, 13
	s_lshl_b32 s3, s60, 11
	s_add_i32 s2, s2, s3
	s_add_i32 s60, s2, 0x10800
	v_lshl_add_u32 v138, v11, 4, v10
	v_lshlrev_b32_e32 v138, 4, v138
	v_add_u32_e32 v139, 0x400, v138
	s_lshl_b32 s2, s56, 13
	v_add_u32_e32 v140, s2, v138
	v_add_u32_e32 v140, 0x10800, v140
	s_add_i32 m0, s60, 0x0
	s_nop 0
	global_load_lds_dwordx4 v138, s[62:63]
	s_add_i32 m0, s60, 0x400
	s_nop 0
	global_load_lds_dwordx4 v139, s[62:63]
	s_add_u32 s62, s62, s64
	s_addc_u32 s63, s63, 0
	s_add_i32 m0, s60, 0x4000
	s_nop 0
	global_load_lds_dwordx4 v138, s[62:63]
	s_add_i32 m0, s60, 0x4400
	s_nop 0
	global_load_lds_dwordx4 v139, s[62:63]
	s_add_u32 s62, s62, s64
	s_addc_u32 s63, s63, 0
	global_load_dwordx4 v[48:51], v134, s[20:21]
	global_load_dwordx4 v[52:55], v134, s[22:23]
	v_add_u32_e32 v134, 64, v134
	s_waitcnt vmcnt(4)
	s_barrier
; __device__ __forceinline__ unsigned pk2(float lo, float hi) { f32x2 v = {lo, hi}; bf16x2_t b = __builtin_convertvector(v, bf16x2_t); return __builtin_bit_cast(unsigned, b); }
; __device__ __forceinline__ float sigmoidf_(float x) { return frcp(1.f + fexp2(-1.4426950408889634f * x)); }
; __device__ __forceinline__ void phase_lora(const Ctx& p, LAS unsigned char* lds) {
;     ...
;         auto tile = [&](const WF& f, int nt) {
;             f32x4 aw = (f32x4){0.f, 0.f, 0.f, 0.f}, aa = aw, ag = aw;
; #pragma unroll
;             for (int ks = 0; ks < 2; ++ks) { aw = __builtin_amdgcn_mfma_f32_16x16x32_bf16(f.w[ks], bx[ks], aw, 0, 0, 0); aa = __builtin_amdgcn_mfma_f32_16x16x32_bf16(f.a[ks], bx[2 + ks], aa, 0, 0, 0); }
; #pragma unroll
;             for (int ks = 0; ks < 4; ++ks) ag = __builtin_amdgcn_mfma_f32_16x16x32_bf16(f.gq[ks], bx[4 + ks], ag, 0, 0, 0);
;             const int c = nt * 16 + 4 * g;
;             f32x4 dec; float av[4];
; #pragma unroll
;             for (int e = 0; e < 4; ++e) {
;                 const float x = f.w0[e] + aw[e];
;                 const float sp = fmaxf(-x, 0.f) + log1pf(expf(-fabsf(x)));
;                 dec[e] = expf(-expf(-sp - 0.5f));
;                 av[e] = sigmoidf_(f.a0[e] + aa[e]);
;             }
;             *(f32x4*)(DEC + (size_t)row * 512 + c) = dec;
;             *(u32x2*)(AB + (size_t)row * 512 + c) = (u32x2){pk2(av[0], av[1]), pk2(av[2], av[3])};
;             *(u32x2*)(GG + (size_t)row * 512 + c) = (u32x2){pk2(ag[0], ag[1]), pk2(ag[2], ag[3])};
;         };
;         WF fa, fb;
;         ldw(fa, 0);
; #pragma unroll 1
;         for (int nt = 0; nt < 32; nt += 2) {
;             ldw(fb, nt + 1);
;             tile(fa, nt);
;             ldw(fa, (nt + 2) & 31);
;             tile(fb, nt + 1);
;         }
	ds_read_b128 v[16:19], v140 offset:0
	ds_read_b128 v[20:23], v140 offset:1024
	ds_read_b128 v[24:27], v140 offset:2048
	ds_read_b128 v[28:31], v140 offset:3072
	ds_read_b128 v[32:35], v140 offset:4096
	ds_read_b128 v[36:39], v140 offset:5120
	ds_read_b128 v[40:43], v140 offset:6144
	ds_read_b128 v[44:47], v140 offset:7168
	s_add_i32 m0, s60, 0x8000
	s_nop 0
	global_load_lds_dwordx4 v138, s[62:63]
	s_add_i32 m0, s60, 0x8400
	s_nop 0
	global_load_lds_dwordx4 v139, s[62:63]
	s_add_u32 s62, s62, s64
	s_addc_u32 s63, s63, 0
	global_load_dwordx4 v[88:91], v134, s[20:21]
	global_load_dwordx4 v[92:95], v134, s[22:23]
	v_add_u32_e32 v134, 64, v134
	s_waitcnt vmcnt(4)
	s_waitcnt lgkmcnt(0)
	v_mfma_f32_16x16x32_bf16 v[96:99], v[16:19], v[184:187], 0
	v_mfma_f32_16x16x32_bf16 v[100:103], v[24:27], v[192:195], 0
	v_mfma_f32_16x16x32_bf16 v[104:107], v[32:35], v[200:203], 0
	v_mfma_f32_16x16x32_bf16 v[96:99], v[20:23], v[188:191], v[96:99]
	v_mfma_f32_16x16x32_bf16 v[100:103], v[28:31], v[196:199], v[100:103]
	v_mfma_f32_16x16x32_bf16 v[104:107], v[36:39], v[204:207], v[104:107]
	v_mfma_f32_16x16x32_bf16 v[104:107], v[40:43], v[208:211], v[104:107]
	v_mfma_f32_16x16x32_bf16 v[104:107], v[44:47], v[212:215], v[104:107]
	s_nop 4
	v_add_f32_e32 v108, v48, v96
	v_add_f32_e32 v109, v49, v97
	v_add_f32_e32 v110, v50, v98
	v_add_f32_e32 v111, v51, v99
	v_add_f32_e32 v112, v52, v100
	v_add_f32_e32 v113, v53, v101
	v_add_f32_e32 v114, v54, v102
	v_add_f32_e32 v115, v55, v103
	v_mul_f32_e32 v108, 0xbfb8aa3b, v108
	v_mul_f32_e32 v109, 0xbfb8aa3b, v109
	v_mul_f32_e32 v110, 0xbfb8aa3b, v110
	v_mul_f32_e32 v111, 0xbfb8aa3b, v111
	v_mul_f32_e32 v112, 0xbfb8aa3b, v112
	v_mul_f32_e32 v113, 0xbfb8aa3b, v113
	v_mul_f32_e32 v114, 0xbfb8aa3b, v114
	v_mul_f32_e32 v115, 0xbfb8aa3b, v115
	v_exp_f32_e32 v108, v108
	v_exp_f32_e32 v109, v109
	v_exp_f32_e32 v110, v110
	v_exp_f32_e32 v111, v111
	v_exp_f32_e32 v112, v112
	v_exp_f32_e32 v113, v113
	v_exp_f32_e32 v114, v114
	v_exp_f32_e32 v115, v115
	v_add_f32_e32 v108, 1.0, v108
	v_add_f32_e32 v109, 1.0, v109
	v_add_f32_e32 v110, 1.0, v110
	v_add_f32_e32 v111, 1.0, v111
	v_add_f32_e32 v112, 1.0, v112
	v_add_f32_e32 v113, 1.0, v113
	v_add_f32_e32 v114, 1.0, v114
	v_add_f32_e32 v115, 1.0, v115
	v_rcp_f32_e32 v108, v108
	v_rcp_f32_e32 v109, v109
	v_rcp_f32_e32 v110, v110
	v_rcp_f32_e32 v111, v111
	v_rcp_f32_e32 v112, v112
	v_rcp_f32_e32 v113, v113
	v_rcp_f32_e32 v114, v114
	v_rcp_f32_e32 v115, v115
	v_mul_f32_e32 v108, 0xbf60028b, v108
	v_mul_f32_e32 v109, 0xbf60028b, v109
	v_mul_f32_e32 v110, 0xbf60028b, v110
	v_mul_f32_e32 v111, 0xbf60028b, v111
	v_cvt_pk_bf16_f32 v116, v112, v113
	v_cvt_pk_bf16_f32 v117, v114, v115
	v_exp_f32_e32 v108, v108
	v_exp_f32_e32 v109, v109
	v_exp_f32_e32 v110, v110
	v_exp_f32_e32 v111, v111
	v_cvt_pk_bf16_f32 v118, v104, v105
	v_cvt_pk_bf16_f32 v119, v106, v107
	global_store_dwordx2 v136, v[116:117], s[44:45]
	global_store_dwordx2 v136, v[118:119], s[46:47]
	global_store_dwordx4 v135, v[108:111], s[54:55]
	v_add_u32_e32 v136, 32, v136
	v_add_u32_e32 v135, 64, v135
	s_waitcnt vmcnt(9)
	s_barrier
	s_mov_b32 s61, 4
.Llora_roll:
	ds_read_b128 v[16:19], v140 offset:16384
	ds_read_b128 v[20:23], v140 offset:17408
	ds_read_b128 v[24:27], v140 offset:18432
	ds_read_b128 v[28:31], v140 offset:19456
	ds_read_b128 v[32:35], v140 offset:20480
	ds_read_b128 v[36:39], v140 offset:21504
	ds_read_b128 v[40:43], v140 offset:22528
	ds_read_b128 v[44:47], v140 offset:23552
	s_add_i32 m0, s60, 0x0
	s_nop 0
	global_load_lds_dwordx4 v138, s[62:63]
	s_add_i32 m0, s60, 0x400
	s_nop 0
	global_load_lds_dwordx4 v139, s[62:63]
	s_add_u32 s62, s62, s64
	s_addc_u32 s63, s63, 0
	global_load_dwordx4 v[120:123], v134, s[20:21]
	global_load_dwordx4 v[124:127], v134, s[22:23]
	v_add_u32_e32 v134, 64, v134
	s_waitcnt vmcnt(7)
	s_waitcnt lgkmcnt(0)
	v_mfma_f32_16x16x32_bf16 v[96:99], v[16:19], v[184:187], 0
	v_mfma_f32_16x16x32_bf16 v[100:103], v[24:27], v[192:195], 0
	v_mfma_f32_16x16x32_bf16 v[104:107], v[32:35], v[200:203], 0
	v_mfma_f32_16x16x32_bf16 v[96:99], v[20:23], v[188:191], v[96:99]
	v_mfma_f32_16x16x32_bf16 v[100:103], v[28:31], v[196:199], v[100:103]
	v_mfma_f32_16x16x32_bf16 v[104:107], v[36:39], v[204:207], v[104:107]
	v_mfma_f32_16x16x32_bf16 v[104:107], v[40:43], v[208:211], v[104:107]
	v_mfma_f32_16x16x32_bf16 v[104:107], v[44:47], v[212:215], v[104:107]
	s_nop 4
	v_add_f32_e32 v108, v88, v96
	v_add_f32_e32 v109, v89, v97
	v_add_f32_e32 v110, v90, v98
	v_add_f32_e32 v111, v91, v99
	v_add_f32_e32 v112, v92, v100
	v_add_f32_e32 v113, v93, v101
	v_add_f32_e32 v114, v94, v102
	v_add_f32_e32 v115, v95, v103
	v_mul_f32_e32 v108, 0xbfb8aa3b, v108
	v_mul_f32_e32 v109, 0xbfb8aa3b, v109
	v_mul_f32_e32 v110, 0xbfb8aa3b, v110
	v_mul_f32_e32 v111, 0xbfb8aa3b, v111
	v_mul_f32_e32 v112, 0xbfb8aa3b, v112
	v_mul_f32_e32 v113, 0xbfb8aa3b, v113
	v_mul_f32_e32 v114, 0xbfb8aa3b, v114
	v_mul_f32_e32 v115, 0xbfb8aa3b, v115
	v_exp_f32_e32 v108, v108
	v_exp_f32_e32 v109, v109
	v_exp_f32_e32 v110, v110
	v_exp_f32_e32 v111, v111
	v_exp_f32_e32 v112, v112
	v_exp_f32_e32 v113, v113
	v_exp_f32_e32 v114, v114
	v_exp_f32_e32 v115, v115
	v_add_f32_e32 v108, 1.0, v108
	v_add_f32_e32 v109, 1.0, v109
	v_add_f32_e32 v110, 1.0, v110
	v_add_f32_e32 v111, 1.0, v111
	v_add_f32_e32 v112, 1.0, v112
	v_add_f32_e32 v113, 1.0, v113
	v_add_f32_e32 v114, 1.0, v114
	v_add_f32_e32 v115, 1.0, v115
	v_rcp_f32_e32 v108, v108
	v_rcp_f32_e32 v109, v109
	v_rcp_f32_e32 v110, v110
	v_rcp_f32_e32 v111, v111
	v_rcp_f32_e32 v112, v112
	v_rcp_f32_e32 v113, v113
	v_rcp_f32_e32 v114, v114
	v_rcp_f32_e32 v115, v115
	v_mul_f32_e32 v108, 0xbf60028b, v108
	v_mul_f32_e32 v109, 0xbf60028b, v109
	v_mul_f32_e32 v110, 0xbf60028b, v110
	v_mul_f32_e32 v111, 0xbf60028b, v111
	v_cvt_pk_bf16_f32 v116, v112, v113
	v_cvt_pk_bf16_f32 v117, v114, v115
	v_exp_f32_e32 v108, v108
	v_exp_f32_e32 v109, v109
	v_exp_f32_e32 v110, v110
	v_exp_f32_e32 v111, v111
	v_cvt_pk_bf16_f32 v118, v104, v105
	v_cvt_pk_bf16_f32 v119, v106, v107
	global_store_dwordx2 v136, v[116:117], s[44:45]
	global_store_dwordx2 v136, v[118:119], s[46:47]
	global_store_dwordx4 v135, v[108:111], s[54:55]
	v_add_u32_e32 v136, 32, v136
	v_add_u32_e32 v135, 64, v135
	s_waitcnt vmcnt(12)
	s_barrier
; __device__ __forceinline__ unsigned pk2(float lo, float hi) { f32x2 v = {lo, hi}; bf16x2_t b = __builtin_convertvector(v, bf16x2_t); return __builtin_bit_cast(unsigned, b); }
; __device__ __forceinline__ float sigmoidf_(float x) { return frcp(1.f + fexp2(-1.4426950408889634f * x)); }
; __device__ __forceinline__ void phase_lora(const Ctx& p, LAS unsigned char* lds) {
;     ...
;         auto tile = [&](const WF& f, int nt) {
;             f32x4 aw = (f32x4){0.f, 0.f, 0.f, 0.f}, aa = aw, ag = aw;
; #pragma unroll
;             for (int ks = 0; ks < 2; ++ks) { aw = __builtin_amdgcn_mfma_f32_16x16x32_bf16(f.w[ks], bx[ks], aw, 0, 0, 0); aa = __builtin_amdgcn_mfma_f32_16x16x32_bf16(f.a[ks], bx[2 + ks], aa, 0, 0, 0); }
; #pragma unroll
;             for (int ks = 0; ks < 4; ++ks) ag = __builtin_amdgcn_mfma_f32_16x16x32_bf16(f.gq[ks], bx[4 + ks], ag, 0, 0, 0);
;             const int c = nt * 16 + 4 * g;
;             f32x4 dec; float av[4];
; #pragma unroll
;             for (int e = 0; e < 4; ++e) {
;                 const float x = f.w0[e] + aw[e];
;                 const float sp = fmaxf(-x, 0.f) + log1pf(expf(-fabsf(x)));
;                 dec[e] = expf(-expf(-sp - 0.5f));
;                 av[e] = sigmoidf_(f.a0[e] + aa[e]);
;             }
;             *(f32x4*)(DEC + (size_t)row * 512 + c) = dec;
;             *(u32x2*)(AB + (size_t)row * 512 + c) = (u32x2){pk2(av[0], av[1]), pk2(av[2], av[3])};
;             *(u32x2*)(GG + (size_t)row * 512 + c) = (u32x2){pk2(ag[0], ag[1]), pk2(ag[2], ag[3])};
;         };
	ds_read_b128 v[16:19], v140 offset:32768
	ds_read_b128 v[20:23], v140 offset:33792
	ds_read_b128 v[24:27], v140 offset:34816
	ds_read_b128 v[28:31], v140 offset:35840
	ds_read_b128 v[32:35], v140 offset:36864
	ds_read_b128 v[36:39], v140 offset:37888
	ds_read_b128 v[40:43], v140 offset:38912
	ds_read_b128 v[44:47], v140 offset:39936
	s_add_i32 m0, s60, 0x4000
	s_nop 0
	global_load_lds_dwordx4 v138, s[62:63]
	s_add_i32 m0, s60, 0x4400
	s_nop 0
	global_load_lds_dwordx4 v139, s[62:63]
	s_add_u32 s62, s62, s64
	s_addc_u32 s63, s63, 0
	global_load_dwordx4 v[48:51], v134, s[20:21]
	global_load_dwordx4 v[52:55], v134, s[22:23]
	v_add_u32_e32 v134, 64, v134
	s_waitcnt vmcnt(7)
	s_waitcnt lgkmcnt(0)
	v_mfma_f32_16x16x32_bf16 v[96:99], v[16:19], v[184:187], 0
	v_mfma_f32_16x16x32_bf16 v[100:103], v[24:27], v[192:195], 0
	v_mfma_f32_16x16x32_bf16 v[104:107], v[32:35], v[200:203], 0
	v_mfma_f32_16x16x32_bf16 v[96:99], v[20:23], v[188:191], v[96:99]
	v_mfma_f32_16x16x32_bf16 v[100:103], v[28:31], v[196:199], v[100:103]
	v_mfma_f32_16x16x32_bf16 v[104:107], v[36:39], v[204:207], v[104:107]
	v_mfma_f32_16x16x32_bf16 v[104:107], v[40:43], v[208:211], v[104:107]
	v_mfma_f32_16x16x32_bf16 v[104:107], v[44:47], v[212:215], v[104:107]
	s_nop 4
	v_add_f32_e32 v108, v120, v96
	v_add_f32_e32 v109, v121, v97
	v_add_f32_e32 v110, v122, v98
	v_add_f32_e32 v111, v123, v99
	v_add_f32_e32 v112, v124, v100
	v_add_f32_e32 v113, v125, v101
	v_add_f32_e32 v114, v126, v102
	v_add_f32_e32 v115, v127, v103
	v_mul_f32_e32 v108, 0xbfb8aa3b, v108
	v_mul_f32_e32 v109, 0xbfb8aa3b, v109
	v_mul_f32_e32 v110, 0xbfb8aa3b, v110
	v_mul_f32_e32 v111, 0xbfb8aa3b, v111
	v_mul_f32_e32 v112, 0xbfb8aa3b, v112
	v_mul_f32_e32 v113, 0xbfb8aa3b, v113
	v_mul_f32_e32 v114, 0xbfb8aa3b, v114
	v_mul_f32_e32 v115, 0xbfb8aa3b, v115
	v_exp_f32_e32 v108, v108
	v_exp_f32_e32 v109, v109
	v_exp_f32_e32 v110, v110
	v_exp_f32_e32 v111, v111
	v_exp_f32_e32 v112, v112
	v_exp_f32_e32 v113, v113
	v_exp_f32_e32 v114, v114
	v_exp_f32_e32 v115, v115
	v_add_f32_e32 v108, 1.0, v108
	v_add_f32_e32 v109, 1.0, v109
	v_add_f32_e32 v110, 1.0, v110
	v_add_f32_e32 v111, 1.0, v111
	v_add_f32_e32 v112, 1.0, v112
	v_add_f32_e32 v113, 1.0, v113
	v_add_f32_e32 v114, 1.0, v114
	v_add_f32_e32 v115, 1.0, v115
	v_rcp_f32_e32 v108, v108
	v_rcp_f32_e32 v109, v109
	v_rcp_f32_e32 v110, v110
	v_rcp_f32_e32 v111, v111
	v_rcp_f32_e32 v112, v112
	v_rcp_f32_e32 v113, v113
	v_rcp_f32_e32 v114, v114
	v_rcp_f32_e32 v115, v115
	v_mul_f32_e32 v108, 0xbf60028b, v108
	v_mul_f32_e32 v109, 0xbf60028b, v109
	v_mul_f32_e32 v110, 0xbf60028b, v110
	v_mul_f32_e32 v111, 0xbf60028b, v111
	v_cvt_pk_bf16_f32 v116, v112, v113
	v_cvt_pk_bf16_f32 v117, v114, v115
	v_exp_f32_e32 v108, v108
	v_exp_f32_e32 v109, v109
	v_exp_f32_e32 v110, v110
	v_exp_f32_e32 v111, v111
	v_cvt_pk_bf16_f32 v118, v104, v105
	v_cvt_pk_bf16_f32 v119, v106, v107
	global_store_dwordx2 v136, v[116:117], s[44:45]
	global_store_dwordx2 v136, v[118:119], s[46:47]
	global_store_dwordx4 v135, v[108:111], s[54:55]
	v_add_u32_e32 v136, 32, v136
	v_add_u32_e32 v135, 64, v135
	s_waitcnt vmcnt(12)
	s_barrier
	ds_read_b128 v[16:19], v140 offset:0
	ds_read_b128 v[20:23], v140 offset:1024
	ds_read_b128 v[24:27], v140 offset:2048
	ds_read_b128 v[28:31], v140 offset:3072
	ds_read_b128 v[32:35], v140 offset:4096
	ds_read_b128 v[36:39], v140 offset:5120
	ds_read_b128 v[40:43], v140 offset:6144
	ds_read_b128 v[44:47], v140 offset:7168
	s_add_i32 m0, s60, 0x8000
	s_nop 0
	global_load_lds_dwordx4 v138, s[62:63]
	s_add_i32 m0, s60, 0x8400
	s_nop 0
	global_load_lds_dwordx4 v139, s[62:63]
	s_add_u32 s62, s62, s64
	s_addc_u32 s63, s63, 0
	global_load_dwordx4 v[88:91], v134, s[20:21]
	global_load_dwordx4 v[92:95], v134, s[22:23]
	v_add_u32_e32 v134, 64, v134
	s_waitcnt vmcnt(7)
	s_waitcnt lgkmcnt(0)
	v_mfma_f32_16x16x32_bf16 v[96:99], v[16:19], v[184:187], 0
	v_mfma_f32_16x16x32_bf16 v[100:103], v[24:27], v[192:195], 0
	v_mfma_f32_16x16x32_bf16 v[104:107], v[32:35], v[200:203], 0
	v_mfma_f32_16x16x32_bf16 v[96:99], v[20:23], v[188:191], v[96:99]
	v_mfma_f32_16x16x32_bf16 v[100:103], v[28:31], v[196:199], v[100:103]
	v_mfma_f32_16x16x32_bf16 v[104:107], v[36:39], v[204:207], v[104:107]
	v_mfma_f32_16x16x32_bf16 v[104:107], v[40:43], v[208:211], v[104:107]
	v_mfma_f32_16x16x32_bf16 v[104:107], v[44:47], v[212:215], v[104:107]
	s_nop 4
	v_add_f32_e32 v108, v48, v96
	v_add_f32_e32 v109, v49, v97
	v_add_f32_e32 v110, v50, v98
	v_add_f32_e32 v111, v51, v99
	v_add_f32_e32 v112, v52, v100
	v_add_f32_e32 v113, v53, v101
	v_add_f32_e32 v114, v54, v102
	v_add_f32_e32 v115, v55, v103
	v_mul_f32_e32 v108, 0xbfb8aa3b, v108
	v_mul_f32_e32 v109, 0xbfb8aa3b, v109
	v_mul_f32_e32 v110, 0xbfb8aa3b, v110
	v_mul_f32_e32 v111, 0xbfb8aa3b, v111
	v_mul_f32_e32 v112, 0xbfb8aa3b, v112
	v_mul_f32_e32 v113, 0xbfb8aa3b, v113
	v_mul_f32_e32 v114, 0xbfb8aa3b, v114
	v_mul_f32_e32 v115, 0xbfb8aa3b, v115
	v_exp_f32_e32 v108, v108
	v_exp_f32_e32 v109, v109
	v_exp_f32_e32 v110, v110
	v_exp_f32_e32 v111, v111
	v_exp_f32_e32 v112, v112
	v_exp_f32_e32 v113, v113
	v_exp_f32_e32 v114, v114
	v_exp_f32_e32 v115, v115
	v_add_f32_e32 v108, 1.0, v108
	v_add_f32_e32 v109, 1.0, v109
	v_add_f32_e32 v110, 1.0, v110
	v_add_f32_e32 v111, 1.0, v111
	v_add_f32_e32 v112, 1.0, v112
	v_add_f32_e32 v113, 1.0, v113
	v_add_f32_e32 v114, 1.0, v114
	v_add_f32_e32 v115, 1.0, v115
	v_rcp_f32_e32 v108, v108
	v_rcp_f32_e32 v109, v109
	v_rcp_f32_e32 v110, v110
	v_rcp_f32_e32 v111, v111
	v_rcp_f32_e32 v112, v112
	v_rcp_f32_e32 v113, v113
	v_rcp_f32_e32 v114, v114
	v_rcp_f32_e32 v115, v115
	v_mul_f32_e32 v108, 0xbf60028b, v108
	v_mul_f32_e32 v109, 0xbf60028b, v109
	v_mul_f32_e32 v110, 0xbf60028b, v110
	v_mul_f32_e32 v111, 0xbf60028b, v111
	v_cvt_pk_bf16_f32 v116, v112, v113
	v_cvt_pk_bf16_f32 v117, v114, v115
	v_exp_f32_e32 v108, v108
	v_exp_f32_e32 v109, v109
	v_exp_f32_e32 v110, v110
	v_exp_f32_e32 v111, v111
	v_cvt_pk_bf16_f32 v118, v104, v105
	v_cvt_pk_bf16_f32 v119, v106, v107
	global_store_dwordx2 v136, v[116:117], s[44:45]
	global_store_dwordx2 v136, v[118:119], s[46:47]
	global_store_dwordx4 v135, v[108:111], s[54:55]
	v_add_u32_e32 v136, 32, v136
	v_add_u32_e32 v135, 64, v135
	s_waitcnt vmcnt(12)
	s_barrier
; __device__ __forceinline__ unsigned pk2(float lo, float hi) { f32x2 v = {lo, hi}; bf16x2_t b = __builtin_convertvector(v, bf16x2_t); return __builtin_bit_cast(unsigned, b); }
; __device__ __forceinline__ float sigmoidf_(float x) { return frcp(1.f + fexp2(-1.4426950408889634f * x)); }
; __device__ __forceinline__ void phase_lora(const Ctx& p, LAS unsigned char* lds) {
;     ...
;         auto tile = [&](const WF& f, int nt) {
;             f32x4 aw = (f32x4){0.f, 0.f, 0.f, 0.f}, aa = aw, ag = aw;
; #pragma unroll
;             for (int ks = 0; ks < 2; ++ks) { aw = __builtin_amdgcn_mfma_f32_16x16x32_bf16(f.w[ks], bx[ks], aw, 0, 0, 0); aa = __builtin_amdgcn_mfma_f32_16x16x32_bf16(f.a[ks], bx[2 + ks], aa, 0, 0, 0); }
; #pragma unroll
;             for (int ks = 0; ks < 4; ++ks) ag = __builtin_amdgcn_mfma_f32_16x16x32_bf16(f.gq[ks], bx[4 + ks], ag, 0, 0, 0);
;             const int c = nt * 16 + 4 * g;
;             f32x4 dec; float av[4];
; #pragma unroll
;             for (int e = 0; e < 4; ++e) {
;                 const float x = f.w0[e] + aw[e];
;                 const float sp = fmaxf(-x, 0.f) + log1pf(expf(-fabsf(x)));
;                 dec[e] = expf(-expf(-sp - 0.5f));
;                 av[e] = sigmoidf_(f.a0[e] + aa[e]);
;             }
;             *(f32x4*)(DEC + (size_t)row * 512 + c) = dec;
;             *(u32x2*)(AB + (size_t)row * 512 + c) = (u32x2){pk2(av[0], av[1]), pk2(av[2], av[3])};
;             *(u32x2*)(GG + (size_t)row * 512 + c) = (u32x2){pk2(ag[0], ag[1]), pk2(ag[2], ag[3])};
;         };
;         WF fa, fb;
;         ldw(fa, 0);
; #pragma unroll 1
;         for (int nt = 0; nt < 32; nt += 2) {
;             ldw(fb, nt + 1);
;             tile(fa, nt);
;             ldw(fa, (nt + 2) & 31);
;             tile(fb, nt + 1);
;         }
	s_sub_u32 s61, s61, 1
	s_cmp_lg_u32 s61, 0
	s_cbranch_scc1 .Llora_roll
	ds_read_b128 v[16:19], v140 offset:16384
	ds_read_b128 v[20:23], v140 offset:17408
	ds_read_b128 v[24:27], v140 offset:18432
	ds_read_b128 v[28:31], v140 offset:19456
	ds_read_b128 v[32:35], v140 offset:20480
	ds_read_b128 v[36:39], v140 offset:21504
	ds_read_b128 v[40:43], v140 offset:22528
	ds_read_b128 v[44:47], v140 offset:23552
	s_add_i32 m0, s60, 0x0
	s_nop 0
	global_load_lds_dwordx4 v138, s[62:63]
	s_add_i32 m0, s60, 0x400
	s_nop 0
	global_load_lds_dwordx4 v139, s[62:63]
	s_add_u32 s62, s62, s64
	s_addc_u32 s63, s63, 0
	global_load_dwordx4 v[120:123], v134, s[20:21]
	global_load_dwordx4 v[124:127], v134, s[22:23]
	v_add_u32_e32 v134, 64, v134
	s_waitcnt vmcnt(7)
	s_waitcnt lgkmcnt(0)
	v_mfma_f32_16x16x32_bf16 v[96:99], v[16:19], v[184:187], 0
	v_mfma_f32_16x16x32_bf16 v[100:103], v[24:27], v[192:195], 0
	v_mfma_f32_16x16x32_bf16 v[104:107], v[32:35], v[200:203], 0
	v_mfma_f32_16x16x32_bf16 v[96:99], v[20:23], v[188:191], v[96:99]
	v_mfma_f32_16x16x32_bf16 v[100:103], v[28:31], v[196:199], v[100:103]
	v_mfma_f32_16x16x32_bf16 v[104:107], v[36:39], v[204:207], v[104:107]
	v_mfma_f32_16x16x32_bf16 v[104:107], v[40:43], v[208:211], v[104:107]
	v_mfma_f32_16x16x32_bf16 v[104:107], v[44:47], v[212:215], v[104:107]
	s_nop 4
	v_add_f32_e32 v108, v88, v96
	v_add_f32_e32 v109, v89, v97
	v_add_f32_e32 v110, v90, v98
	v_add_f32_e32 v111, v91, v99
	v_add_f32_e32 v112, v92, v100
	v_add_f32_e32 v113, v93, v101
	v_add_f32_e32 v114, v94, v102
	v_add_f32_e32 v115, v95, v103
	v_mul_f32_e32 v108, 0xbfb8aa3b, v108
	v_mul_f32_e32 v109, 0xbfb8aa3b, v109
	v_mul_f32_e32 v110, 0xbfb8aa3b, v110
	v_mul_f32_e32 v111, 0xbfb8aa3b, v111
	v_mul_f32_e32 v112, 0xbfb8aa3b, v112
	v_mul_f32_e32 v113, 0xbfb8aa3b, v113
	v_mul_f32_e32 v114, 0xbfb8aa3b, v114
	v_mul_f32_e32 v115, 0xbfb8aa3b, v115
	v_exp_f32_e32 v108, v108
	v_exp_f32_e32 v109, v109
	v_exp_f32_e32 v110, v110
	v_exp_f32_e32 v111, v111
	v_exp_f32_e32 v112, v112
	v_exp_f32_e32 v113, v113
	v_exp_f32_e32 v114, v114
	v_exp_f32_e32 v115, v115
	v_add_f32_e32 v108, 1.0, v108
	v_add_f32_e32 v109, 1.0, v109
	v_add_f32_e32 v110, 1.0, v110
	v_add_f32_e32 v111, 1.0, v111
	v_add_f32_e32 v112, 1.0, v112
	v_add_f32_e32 v113, 1.0, v113
	v_add_f32_e32 v114, 1.0, v114
	v_add_f32_e32 v115, 1.0, v115
	v_rcp_f32_e32 v108, v108
	v_rcp_f32_e32 v109, v109
	v_rcp_f32_e32 v110, v110
	v_rcp_f32_e32 v111, v111
	v_rcp_f32_e32 v112, v112
	v_rcp_f32_e32 v113, v113
	v_rcp_f32_e32 v114, v114
	v_rcp_f32_e32 v115, v115
	v_mul_f32_e32 v108, 0xbf60028b, v108
	v_mul_f32_e32 v109, 0xbf60028b, v109
	v_mul_f32_e32 v110, 0xbf60028b, v110
	v_mul_f32_e32 v111, 0xbf60028b, v111
	v_cvt_pk_bf16_f32 v116, v112, v113
	v_cvt_pk_bf16_f32 v117, v114, v115
	v_exp_f32_e32 v108, v108
	v_exp_f32_e32 v109, v109
	v_exp_f32_e32 v110, v110
	v_exp_f32_e32 v111, v111
	v_cvt_pk_bf16_f32 v118, v104, v105
	v_cvt_pk_bf16_f32 v119, v106, v107
	global_store_dwordx2 v136, v[116:117], s[44:45]
	global_store_dwordx2 v136, v[118:119], s[46:47]
	global_store_dwordx4 v135, v[108:111], s[54:55]
	v_add_u32_e32 v136, 32, v136
	v_add_u32_e32 v135, 64, v135
	s_waitcnt vmcnt(12)
	s_barrier
	ds_read_b128 v[16:19], v140 offset:32768
	ds_read_b128 v[20:23], v140 offset:33792
	ds_read_b128 v[24:27], v140 offset:34816
	ds_read_b128 v[28:31], v140 offset:35840
	ds_read_b128 v[32:35], v140 offset:36864
	ds_read_b128 v[36:39], v140 offset:37888
	ds_read_b128 v[40:43], v140 offset:38912
	ds_read_b128 v[44:47], v140 offset:39936
	global_load_dwordx4 v[48:51], v134, s[20:21]
	global_load_dwordx4 v[52:55], v134, s[22:23]
	v_add_u32_e32 v134, 64, v134
	s_waitcnt vmcnt(5)
	s_waitcnt lgkmcnt(0)
	v_mfma_f32_16x16x32_bf16 v[96:99], v[16:19], v[184:187], 0
	v_mfma_f32_16x16x32_bf16 v[100:103], v[24:27], v[192:195], 0
	v_mfma_f32_16x16x32_bf16 v[104:107], v[32:35], v[200:203], 0
	v_mfma_f32_16x16x32_bf16 v[96:99], v[20:23], v[188:191], v[96:99]
	v_mfma_f32_16x16x32_bf16 v[100:103], v[28:31], v[196:199], v[100:103]
	v_mfma_f32_16x16x32_bf16 v[104:107], v[36:39], v[204:207], v[104:107]
	v_mfma_f32_16x16x32_bf16 v[104:107], v[40:43], v[208:211], v[104:107]
	v_mfma_f32_16x16x32_bf16 v[104:107], v[44:47], v[212:215], v[104:107]
	s_nop 4
	v_add_f32_e32 v108, v120, v96
	v_add_f32_e32 v109, v121, v97
	v_add_f32_e32 v110, v122, v98
	v_add_f32_e32 v111, v123, v99
	v_add_f32_e32 v112, v124, v100
	v_add_f32_e32 v113, v125, v101
	v_add_f32_e32 v114, v126, v102
	v_add_f32_e32 v115, v127, v103
	v_mul_f32_e32 v108, 0xbfb8aa3b, v108
	v_mul_f32_e32 v109, 0xbfb8aa3b, v109
	v_mul_f32_e32 v110, 0xbfb8aa3b, v110
	v_mul_f32_e32 v111, 0xbfb8aa3b, v111
	v_mul_f32_e32 v112, 0xbfb8aa3b, v112
	v_mul_f32_e32 v113, 0xbfb8aa3b, v113
	v_mul_f32_e32 v114, 0xbfb8aa3b, v114
	v_mul_f32_e32 v115, 0xbfb8aa3b, v115
	v_exp_f32_e32 v108, v108
	v_exp_f32_e32 v109, v109
	v_exp_f32_e32 v110, v110
	v_exp_f32_e32 v111, v111
	v_exp_f32_e32 v112, v112
	v_exp_f32_e32 v113, v113
	v_exp_f32_e32 v114, v114
	v_exp_f32_e32 v115, v115
	v_add_f32_e32 v108, 1.0, v108
	v_add_f32_e32 v109, 1.0, v109
	v_add_f32_e32 v110, 1.0, v110
	v_add_f32_e32 v111, 1.0, v111
	v_add_f32_e32 v112, 1.0, v112
	v_add_f32_e32 v113, 1.0, v113
	v_add_f32_e32 v114, 1.0, v114
	v_add_f32_e32 v115, 1.0, v115
	v_rcp_f32_e32 v108, v108
	v_rcp_f32_e32 v109, v109
	v_rcp_f32_e32 v110, v110
	v_rcp_f32_e32 v111, v111
	v_rcp_f32_e32 v112, v112
	v_rcp_f32_e32 v113, v113
	v_rcp_f32_e32 v114, v114
	v_rcp_f32_e32 v115, v115
	v_mul_f32_e32 v108, 0xbf60028b, v108
	v_mul_f32_e32 v109, 0xbf60028b, v109
	v_mul_f32_e32 v110, 0xbf60028b, v110
	v_mul_f32_e32 v111, 0xbf60028b, v111
	v_cvt_pk_bf16_f32 v116, v112, v113
	v_cvt_pk_bf16_f32 v117, v114, v115
	v_exp_f32_e32 v108, v108
	v_exp_f32_e32 v109, v109
	v_exp_f32_e32 v110, v110
	v_exp_f32_e32 v111, v111
	v_cvt_pk_bf16_f32 v118, v104, v105
	v_cvt_pk_bf16_f32 v119, v106, v107
	global_store_dwordx2 v136, v[116:117], s[44:45]
	global_store_dwordx2 v136, v[118:119], s[46:47]
	global_store_dwordx4 v135, v[108:111], s[54:55]
	v_add_u32_e32 v136, 32, v136
	v_add_u32_e32 v135, 64, v135
	s_waitcnt vmcnt(10)
	s_barrier
; __device__ __forceinline__ unsigned pk2(float lo, float hi) { f32x2 v = {lo, hi}; bf16x2_t b = __builtin_convertvector(v, bf16x2_t); return __builtin_bit_cast(unsigned, b); }
; __device__ __forceinline__ float sigmoidf_(float x) { return frcp(1.f + fexp2(-1.4426950408889634f * x)); }
; __device__ __forceinline__ void phase_lora(const Ctx& p, LAS unsigned char* lds) {
;     ...
;         auto tile = [&](const WF& f, int nt) {
;             f32x4 aw = (f32x4){0.f, 0.f, 0.f, 0.f}, aa = aw, ag = aw;
; #pragma unroll
;             for (int ks = 0; ks < 2; ++ks) { aw = __builtin_amdgcn_mfma_f32_16x16x32_bf16(f.w[ks], bx[ks], aw, 0, 0, 0); aa = __builtin_amdgcn_mfma_f32_16x16x32_bf16(f.a[ks], bx[2 + ks], aa, 0, 0, 0); }
; #pragma unroll
;             for (int ks = 0; ks < 4; ++ks) ag = __builtin_amdgcn_mfma_f32_16x16x32_bf16(f.gq[ks], bx[4 + ks], ag, 0, 0, 0);
;             const int c = nt * 16 + 4 * g;
;             f32x4 dec; float av[4];
; #pragma unroll
;             for (int e = 0; e < 4; ++e) {
;                 const float x = f.w0[e] + aw[e];
;                 const float sp = fmaxf(-x, 0.f) + log1pf(expf(-fabsf(x)));
;                 dec[e] = expf(-expf(-sp - 0.5f));
;                 av[e] = sigmoidf_(f.a0[e] + aa[e]);
;             }
;             *(f32x4*)(DEC + (size_t)row * 512 + c) = dec;
;             *(u32x2*)(AB + (size_t)row * 512 + c) = (u32x2){pk2(av[0], av[1]), pk2(av[2], av[3])};
;             *(u32x2*)(GG + (size_t)row * 512 + c) = (u32x2){pk2(ag[0], ag[1]), pk2(ag[2], ag[3])};
;         };
;         WF fa, fb;
;         ldw(fa, 0);
; #pragma unroll 1
;         for (int nt = 0; nt < 32; nt += 2) {
;             ldw(fb, nt + 1);
;             tile(fa, nt);
;             ldw(fa, (nt + 2) & 31);
;             tile(fb, nt + 1);
;         }
;         asm volatile("s_waitcnt lgkmcnt(0)" ::: "memory");
;     }
	ds_read_b128 v[16:19], v140 offset:0
	ds_read_b128 v[20:23], v140 offset:1024
	ds_read_b128 v[24:27], v140 offset:2048
	ds_read_b128 v[28:31], v140 offset:3072
	ds_read_b128 v[32:35], v140 offset:4096
	ds_read_b128 v[36:39], v140 offset:5120
	ds_read_b128 v[40:43], v140 offset:6144
	ds_read_b128 v[44:47], v140 offset:7168
	s_waitcnt vmcnt(3)
	s_waitcnt lgkmcnt(0)
	v_mfma_f32_16x16x32_bf16 v[96:99], v[16:19], v[184:187], 0
	v_mfma_f32_16x16x32_bf16 v[100:103], v[24:27], v[192:195], 0
	v_mfma_f32_16x16x32_bf16 v[104:107], v[32:35], v[200:203], 0
	v_mfma_f32_16x16x32_bf16 v[96:99], v[20:23], v[188:191], v[96:99]
	v_mfma_f32_16x16x32_bf16 v[100:103], v[28:31], v[196:199], v[100:103]
	v_mfma_f32_16x16x32_bf16 v[104:107], v[36:39], v[204:207], v[104:107]
	v_mfma_f32_16x16x32_bf16 v[104:107], v[40:43], v[208:211], v[104:107]
	v_mfma_f32_16x16x32_bf16 v[104:107], v[44:47], v[212:215], v[104:107]
	s_nop 4
	v_add_f32_e32 v108, v48, v96
	v_add_f32_e32 v109, v49, v97
	v_add_f32_e32 v110, v50, v98
	v_add_f32_e32 v111, v51, v99
	v_add_f32_e32 v112, v52, v100
	v_add_f32_e32 v113, v53, v101
	v_add_f32_e32 v114, v54, v102
	v_add_f32_e32 v115, v55, v103
	v_mul_f32_e32 v108, 0xbfb8aa3b, v108
	v_mul_f32_e32 v109, 0xbfb8aa3b, v109
	v_mul_f32_e32 v110, 0xbfb8aa3b, v110
	v_mul_f32_e32 v111, 0xbfb8aa3b, v111
	v_mul_f32_e32 v112, 0xbfb8aa3b, v112
	v_mul_f32_e32 v113, 0xbfb8aa3b, v113
	v_mul_f32_e32 v114, 0xbfb8aa3b, v114
	v_mul_f32_e32 v115, 0xbfb8aa3b, v115
	v_exp_f32_e32 v108, v108
	v_exp_f32_e32 v109, v109
	v_exp_f32_e32 v110, v110
	v_exp_f32_e32 v111, v111
	v_exp_f32_e32 v112, v112
	v_exp_f32_e32 v113, v113
	v_exp_f32_e32 v114, v114
	v_exp_f32_e32 v115, v115
	v_add_f32_e32 v108, 1.0, v108
	v_add_f32_e32 v109, 1.0, v109
	v_add_f32_e32 v110, 1.0, v110
	v_add_f32_e32 v111, 1.0, v111
	v_add_f32_e32 v112, 1.0, v112
	v_add_f32_e32 v113, 1.0, v113
	v_add_f32_e32 v114, 1.0, v114
	v_add_f32_e32 v115, 1.0, v115
	v_rcp_f32_e32 v108, v108
	v_rcp_f32_e32 v109, v109
	v_rcp_f32_e32 v110, v110
	v_rcp_f32_e32 v111, v111
	v_rcp_f32_e32 v112, v112
	v_rcp_f32_e32 v113, v113
	v_rcp_f32_e32 v114, v114
	v_rcp_f32_e32 v115, v115
	v_mul_f32_e32 v108, 0xbf60028b, v108
	v_mul_f32_e32 v109, 0xbf60028b, v109
	v_mul_f32_e32 v110, 0xbf60028b, v110
	v_mul_f32_e32 v111, 0xbf60028b, v111
	v_cvt_pk_bf16_f32 v116, v112, v113
	v_cvt_pk_bf16_f32 v117, v114, v115
	v_exp_f32_e32 v108, v108
	v_exp_f32_e32 v109, v109
	v_exp_f32_e32 v110, v110
	v_exp_f32_e32 v111, v111
	v_cvt_pk_bf16_f32 v118, v104, v105
	v_cvt_pk_bf16_f32 v119, v106, v107
	global_store_dwordx2 v136, v[116:117], s[44:45]
	global_store_dwordx2 v136, v[118:119], s[46:47]
	global_store_dwordx4 v135, v[108:111], s[54:55]
	v_add_u32_e32 v136, 32, v136
	v_add_u32_e32 v135, 64, v135
	s_cmp_lt_u32 s28, 32
	s_cbranch_scc0 .Llora_done
	s_mov_b32 s57, 1
	s_lshr_b32 s2, s28, 2
	s_add_i32 s26, s2, 0x400
	s_branch .Llora_item
; __device__ __forceinline__ unsigned pk2(float lo, float hi) { f32x2 v = {lo, hi}; bf16x2_t b = __builtin_convertvector(v, bf16x2_t); return __builtin_bit_cast(unsigned, b); }
; __device__ __forceinline__ void phase_lora(const Ctx& p, LAS unsigned char* lds) {
;     ...
;         auto ldw = [&](WF& f, int nt) {
;             const int n = nt * 16 + q, c = nt * 16 + 4 * g;
; #pragma unroll
;             for (int ks = 0; ks < 2; ++ks) { f.w[ks] = *(const bf16x8*)(w2T + n * 64 + ks * 32 + 8 * g); f.a[ks] = *(const bf16x8*)(a2T + n * 64 + ks * 32 + 8 * g); }
; #pragma unroll
;             for (int ks = 0; ks < 4; ++ks) f.gq[ks] = *(const bf16x8*)(g2T + n * 128 + ks * 32 + 8 * g);
;             f.w0 = *(const f32x4*)(p.in(18) + c); f.a0 = *(const f32x4*)(p.in(20) + c);
;         };
;         auto tile = [&](const WF& f, int nt) {
;             f32x4 aw = (f32x4){0.f, 0.f, 0.f, 0.f}, aa = aw, ag = aw;
; #pragma unroll
;             for (int ks = 0; ks < 2; ++ks) { aw = __builtin_amdgcn_mfma_f32_16x16x32_bf16(f.w[ks], bx[ks], aw, 0, 0, 0); aa = __builtin_amdgcn_mfma_f32_16x16x32_bf16(f.a[ks], bx[2 + ks], aa, 0, 0, 0); }
; #pragma unroll
;             for (int ks = 0; ks < 4; ++ks) ag = __builtin_amdgcn_mfma_f32_16x16x32_bf16(f.gq[ks], bx[4 + ks], ag, 0, 0, 0);
;             const int c = nt * 16 + 4 * g;
;             f32x4 dec; float av[4];
; #pragma unroll
;             for (int e = 0; e < 4; ++e) {
;                 const float x = f.w0[e] + aw[e];
;                 const float sp = fmaxf(-x, 0.f) + log1pf(expf(-fabsf(x)));
;                 dec[e] = expf(-expf(-sp - 0.5f));
;                 av[e] = sigmoidf_(f.a0[e] + aa[e]);
;             }
;             *(f32x4*)(DEC + (size_t)row * 512 + c) = dec;
;             *(u32x2*)(AB + (size_t)row * 512 + c) = (u32x2){pk2(av[0], av[1]), pk2(av[2], av[3])};
;             *(u32x2*)(GG + (size_t)row * 512 + c) = (u32x2){pk2(ag[0], ag[1]), pk2(ag[2], ag[3])};
;         };
; __device__ __forceinline__ void xcd_barrier(const XcdBarrier& b) {
;     asm volatile("s_waitcnt vmcnt(0)" ::: "memory");
;     __syncthreads();
;     if (threadIdx.x == 0) {
;         unsigned* bar = b.bar;
;         __builtin_amdgcn_s_waitcnt(0);
;         unsigned nloc = b.st[0], nx = b.st[1];
;         if (nloc == 0u) { xcd_barrier_complete(bar, b.x, nloc, nx); b.st[0] = nloc; b.st[1] = nx; }
;         const unsigned old = xb_add(&bar[XB_XSUB(b.x)], 1u);
.Llora_single:
	s_and_b32 s2, s28, 3
	s_lshl_b32 s2, s2, 3
	s_add_i32 s2, s2, s27
	s_lshl_b32 s3, s2, 11
	v_add_u32_e32 v132, s3, v132
	s_lshl_b32 s3, s2, 12
	v_add_u32_e32 v133, s3, v133
	s_lshl_b32 s3, s2, 6
	v_add_u32_e32 v134, s3, v134
	v_add_u32_e32 v135, s3, v135
	s_lshl_b32 s3, s2, 5
	v_add_u32_e32 v136, s3, v136
	global_load_dwordx4 v[16:19], v132, s[24:25]
	global_load_dwordx4 v[20:23], v132, s[24:25] offset:1024
	global_load_dwordx4 v[24:27], v132, s[40:41]
	global_load_dwordx4 v[28:31], v132, s[40:41] offset:1024
	global_load_dwordx4 v[32:35], v133, s[42:43]
	global_load_dwordx4 v[36:39], v133, s[42:43] offset:1024
	global_load_dwordx4 v[40:43], v133, s[42:43] offset:2048
	global_load_dwordx4 v[44:47], v133, s[42:43] offset:3072
	global_load_dwordx4 v[48:51], v134, s[20:21]
	global_load_dwordx4 v[52:55], v134, s[22:23]
	s_waitcnt lgkmcnt(0)
	s_waitcnt vmcnt(0)
	v_mfma_f32_16x16x32_bf16 v[96:99], v[16:19], v[184:187], 0
	v_mfma_f32_16x16x32_bf16 v[100:103], v[24:27], v[192:195], 0
	v_mfma_f32_16x16x32_bf16 v[104:107], v[32:35], v[200:203], 0
	v_mfma_f32_16x16x32_bf16 v[96:99], v[20:23], v[188:191], v[96:99]
	v_mfma_f32_16x16x32_bf16 v[100:103], v[28:31], v[196:199], v[100:103]
	v_mfma_f32_16x16x32_bf16 v[104:107], v[36:39], v[204:207], v[104:107]
	v_mfma_f32_16x16x32_bf16 v[104:107], v[40:43], v[208:211], v[104:107]
	v_mfma_f32_16x16x32_bf16 v[104:107], v[44:47], v[212:215], v[104:107]
	v_add_u32_e32 v132, 0x800, v132
	v_add_u32_e32 v133, 0x1000, v133
	v_add_u32_e32 v134, 64, v134
	s_nop 4
	v_add_f32_e32 v108, v48, v96
	v_add_f32_e32 v109, v49, v97
	v_add_f32_e32 v110, v50, v98
	v_add_f32_e32 v111, v51, v99
	v_add_f32_e32 v112, v52, v100
	v_add_f32_e32 v113, v53, v101
	v_add_f32_e32 v114, v54, v102
	v_add_f32_e32 v115, v55, v103
	v_mul_f32_e32 v108, 0xbfb8aa3b, v108
	v_mul_f32_e32 v109, 0xbfb8aa3b, v109
	v_mul_f32_e32 v110, 0xbfb8aa3b, v110
	v_mul_f32_e32 v111, 0xbfb8aa3b, v111
	v_mul_f32_e32 v112, 0xbfb8aa3b, v112
	v_mul_f32_e32 v113, 0xbfb8aa3b, v113
	v_mul_f32_e32 v114, 0xbfb8aa3b, v114
	v_mul_f32_e32 v115, 0xbfb8aa3b, v115
	v_exp_f32_e32 v108, v108
	v_exp_f32_e32 v109, v109
	v_exp_f32_e32 v110, v110
	v_exp_f32_e32 v111, v111
	v_exp_f32_e32 v112, v112
	v_exp_f32_e32 v113, v113
	v_exp_f32_e32 v114, v114
	v_exp_f32_e32 v115, v115
	v_add_f32_e32 v108, 1.0, v108
	v_add_f32_e32 v109, 1.0, v109
	v_add_f32_e32 v110, 1.0, v110
	v_add_f32_e32 v111, 1.0, v111
	v_add_f32_e32 v112, 1.0, v112
	v_add_f32_e32 v113, 1.0, v113
	v_add_f32_e32 v114, 1.0, v114
	v_add_f32_e32 v115, 1.0, v115
	v_rcp_f32_e32 v108, v108
	v_rcp_f32_e32 v109, v109
	v_rcp_f32_e32 v110, v110
	v_rcp_f32_e32 v111, v111
	v_rcp_f32_e32 v112, v112
	v_rcp_f32_e32 v113, v113
	v_rcp_f32_e32 v114, v114
	v_rcp_f32_e32 v115, v115
	v_mul_f32_e32 v108, 0xbf60028b, v108
	v_mul_f32_e32 v109, 0xbf60028b, v109
	v_mul_f32_e32 v110, 0xbf60028b, v110
	v_mul_f32_e32 v111, 0xbf60028b, v111
	v_cvt_pk_bf16_f32 v116, v112, v113
	v_cvt_pk_bf16_f32 v117, v114, v115
	v_exp_f32_e32 v108, v108
	v_exp_f32_e32 v109, v109
	v_exp_f32_e32 v110, v110
	v_exp_f32_e32 v111, v111
	v_cvt_pk_bf16_f32 v118, v104, v105
	v_cvt_pk_bf16_f32 v119, v106, v107
	global_store_dwordx2 v136, v[116:117], s[44:45]
	global_store_dwordx2 v136, v[118:119], s[46:47]
	global_store_dwordx4 v135, v[108:111], s[54:55]
	v_add_u32_e32 v136, 32, v136
	v_add_u32_e32 v135, 64, v135
	s_branch .Llora_done
.Llora_done:
	s_nop 0
.LBB0_1564:
	s_cmp_gt_i32 s37, 6
	s_cselect_b64 s[2:3], -1, 0
	s_and_b64 s[4:5], s[10:11], s[2:3]
	s_andn2_b64 vcc, exec, s[4:5]
	s_cbranch_vccnz .LBB0_1618
	s_waitcnt vmcnt(0)
	v_readlane_b32 s0, v238, 0
	v_readlane_b32 s1, v238, 1
	s_waitcnt vmcnt(0) lgkmcnt(0)
	s_barrier
	s_and_saveexec_b64 s[4:5], s[0:1]
	s_cbranch_execz .LBB0_1617
	s_add_i32 s6, 0, 0x23800
	v_mov_b32_e32 v0, s6
	s_waitcnt vmcnt(0) expcnt(0) lgkmcnt(0)
	ds_read_b32 v2, v0
	s_add_i32 s6, 0, 0x23804
	v_mov_b32_e32 v0, s6
	ds_read_b32 v0, v0
	s_waitcnt lgkmcnt(1)
	v_cmp_ne_u32_e32 vcc, 0, v2
	s_cbranch_vccnz .LBB0_1581
	s_add_u32 s6, s30, 0x3181200
	s_addc_u32 s7, s31, 0
	s_add_u32 s8, s30, 0x3181400
	s_addc_u32 s9, s31, 0
	s_add_u32 s10, s30, 0x3181500
	s_addc_u32 s11, s31, 0
	s_add_u32 s12, s30, 0x3181600
	s_addc_u32 s13, s31, 0
	s_add_u32 s14, s30, 0x3181700
	s_addc_u32 s15, s31, 0
	s_add_u32 s16, s30, 0x3181800
	s_addc_u32 s17, s31, 0
	s_add_u32 s18, s30, 0x3181900
	s_addc_u32 s19, s31, 0
	s_add_u32 s20, s30, 0x3181a00
	s_addc_u32 s21, s31, 0
	s_add_u32 s22, s30, 0x3181b00
	s_addc_u32 s23, s31, 0
	s_add_u32 s24, s30, 0x3181c00
	s_addc_u32 s25, s31, 0
	s_add_u32 s26, s30, 0x3181d00
	s_addc_u32 s27, s31, 0
	s_add_u32 s40, s30, 0x3181e00
	s_addc_u32 s41, s31, 0
	s_add_u32 s42, s30, 0x3181f00
	s_addc_u32 s43, s31, 0
	s_add_u32 s44, s30, 0x3182000
	s_addc_u32 s45, s31, 0
	s_add_u32 s46, s30, 0x3182100
	s_addc_u32 s47, s31, 0
	s_add_u32 s48, s30, 0x3182200
	s_addc_u32 s49, s31, 0
	s_mul_i32 s33, s39, s73
	s_add_u32 s50, s30, 0x3182300
	s_mul_i32 s33, s33, s38
	s_addc_u32 s51, s31, 0
	s_mov_b32 s34, 1
	v_mov_b32_e32 v16, 0
	s_branch .LBB0_1569
